# WG stagger variant: 4 groups (blockIdx bits 3,4; 0/1.9/3.7/5.6us) in phases 1 and 8, 2 groups 7us in phases 6 and 11
# speedup vs baseline: 1.0114x; 1.0114x over previous
;   DI bf16_t* wt_in0() const { return (bf16_t*)(ws + OFF_WT_IN0); }
;   DI bf16_t* h() const { return (bf16_t*)(ws + OFF_H); }
; DI void phase_gemm_in0(const Params& p, char* smem) {
;   u32x4 ra[4], rb[4]; bool pre = false;
;   for (int t = blockIdx.x; t < 64 * 16; t += gridDim.x) {
;     const int mt = t & 63, nt = t >> 6, tn = t + gridDim.x;
;     const bool has_next = tn < 64 * 16;
;     const GTile tl{p.h(), D, p.wt_in0(), D, D, mt * 256, nt * 256}, nx{p.h(), D, p.wt_in0(), D, D, (tn & 63) * 256, (tn >> 6) * 256};
.Lgs_185:
	s_or_b64 exec, exec, s[0:1]
	s_bitcmp1_b32 s84, 3
	s_cbranch_scc0 .Lstag_1_0
	s_sleep 64
.Lstag_1_0:
	s_bitcmp1_b32 s84, 4
	s_cbranch_scc0 .Lstag_1_1
	s_sleep 127
